# MERGE_0 rs_fill: skip the iterations that recompute the same unit's rsqrt table (3 gates per unit)
# speedup vs baseline: 1.0087x; 1.0087x over previous
; #define LAS __attribute__((address_space(3)))
; __device__ __forceinline__ int ltid() { int t = threadIdx.x; asm volatile("" : "+v"(t)); return t; }
; template <int PH, int SUB> __device__ __forceinline__ void rs_fill(LAS unsigned char* lds, const Epi& E) {
;     ...
;         const int tidx = ltid();
;         const float* ssq = (const float*)(E.ws + OFF_SSQ + (kind == K_FFI ? SSQ_BYTES : (kind == K_PLE ? 2 * SSQ_BYTES : 0)));
;         LAS float* tab = (LAS float*)(lds + STAGE_BYTES + 16);
;         for (int i = 0; i < 12; ++i) { Unit u; if (!sched_next<PH, SUB>(E.ws, E.layer, i, u)) break;
;             const int r = tidx >> 1, hf = tidx & 1; const size_t row = (size_t)(u.pm * 256 + r); f32x4 a, b;
.LBB0_857:
	s_or_b64 exec, exec, s[2:3]
	v_readlane_b32 s2, v233, 5
	v_readlane_b32 s3, v233, 6
	s_waitcnt lgkmcnt(0)
	s_barrier
	s_load_dwordx4 s[8:11], s[2:3], 0xc8
	v_mov_b32_e32 v0, v186
	v_readlane_b32 s4, v231, 56
	v_and_b32_e32 v9, 1, v0
	s_waitcnt lgkmcnt(0)
	s_add_u32 s2, s10, 0xa800000
	v_ashrrev_i32_e32 v8, 1, v0
	v_lshlrev_b32_e32 v0, 16, v9
	s_addc_u32 s3, s11, 0
	v_or_b32_e32 v2, 0x8000, v0
	v_mov_b32_e32 v3, v1
	s_mov_b32 s14, 0
	s_mov_b32 s100, -1
	v_cmp_eq_u32_e64 s[6:7], 0, v9
	v_lshl_add_u32 v9, v8, 2, s4
	s_branch .LBB0_860

; template <int PH, int SUB> __device__ __forceinline__ bool sched_next(unsigned char* ws, int layer, int i, Unit& u, const void* ug = nullptr) {
;     ...
;     if constexpr (PH == PH_MERGE) { const int ui = i / 3, r = i % 3, L = ui * G + c; if (L >= 512) return false; tile_map(L, 128, 4, u.pm, u.pn); u.aux = r; u.ord = ui;
; template <int PH, int SUB> __device__ __forceinline__ void rs_fill(LAS unsigned char* lds, const Epi& E) {
;     ...
;         for (int i = 0; i < 12; ++i) { Unit u; if (!sched_next<PH, SUB>(E.ws, E.layer, i, u)) break;
;             const int r = tidx >> 1, hf = tidx & 1; const size_t row = (size_t)(u.pm * 256 + r); f32x4 a, b;
;             { unsigned* pa = (unsigned*)(ssq + ((size_t)(2 * hf) * T_TOK + row) * 4); unsigned* pb = (unsigned*)(ssq + ((size_t)(2 * hf + 1) * T_TOK + row) * 4);
; #pragma unroll
;               for (int j = 0; j < 4; ++j) { a[j] = __uint_as_float(__hip_atomic_load(pa + j, __ATOMIC_RELAXED, __HIP_MEMORY_SCOPE_AGENT)); b[j] = __uint_as_float(__hip_atomic_load(pb + j, __ATOMIC_RELAXED, __HIP_MEMORY_SCOPE_AGENT)); } }
;             float t = ((a[0] + a[1]) + (a[2] + a[3])) + ((b[0] + b[1]) + (b[2] + b[3])); t += __shfl_xor(t, 1);
;             if (hf == 0) tab[u.ord * 256 + r] = rsqrtf(t * (1.0f / 1024.0f) + 1e-6f); }
.LBB0_860:
	s_mul_i32 s4, s14, 0xab
	s_bfe_u32 s15, s4, 0x70009
	s_mul_i32 s16, s56, s15
	s_add_i32 s16, s16, s72
	s_cmpk_gt_i32 s16, 0x1ff
	s_mov_b64 s[12:13], -1
	s_cbranch_scc1 .LBB0_859
	s_cmp_eq_u32 s15, s100
	s_cbranch_scc1 .LBB0_858
	s_mov_b32 s100, s15
	s_ashr_i32 s4, s16, 31
	s_lshr_b32 s4, s4, 29
	s_add_i32 s4, s16, s4
	s_ashr_i32 s5, s4, 3
	s_and_b32 s4, s4, -8
	s_sub_i32 s4, s16, s4
	s_lshr_b32 s12, s4, 31
	s_or_b32 s12, s12, 64
	s_mul_i32 s4, s12, s4
	s_add_i32 s4, s4, s5
	s_ashr_i32 s5, s4, 31
	s_lshr_b32 s5, s5, 27
	s_add_i32 s5, s4, s5
	s_ashr_i32 s12, s5, 5
	s_lshl_b32 s12, s12, 3
	s_sub_i32 s13, 0x80, s12
	s_min_u32 s13, s13, 8
	s_andn2_b32 s5, s5, 31
	s_sub_i32 s16, s4, s5
	s_waitcnt lgkmcnt(0)
	v_cvt_f32_ubyte0_e32 v11, s13
	v_cvt_f32_i32_e32 v10, s16
	v_rcp_iflag_f32_e32 v12, v11
	s_ashr_i32 s4, s16, 30
	s_or_b32 s17, s4, 1
	v_cmp_lt_i32_e32 vcc, v191, v192
	v_mul_f32_e32 v12, v10, v12
	v_trunc_f32_e32 v12, v12
	v_fma_f32 v10, -v12, v11, v10
	v_cvt_i32_f32_e32 v12, v12
	v_cmp_ge_f32_e64 s[4:5], |v10|, v11
	s_and_b64 s[4:5], s[4:5], exec
	s_cselect_b32 s4, s17, 0
	v_readfirstlane_b32 s5, v12
	s_add_i32 s4, s5, s4
	s_mul_i32 s4, s4, s13
	s_sub_i32 s4, s16, s4
	s_sext_i32_i8 s4, s4
	s_add_i32 s12, s12, s4
	v_lshl_add_u32 v10, s12, 8, v8
	v_ashrrev_i32_e32 v11, 31, v10
	v_lshl_add_u64 v[12:13], v[10:11], 0, v[0:1]
	v_lshl_add_u64 v[10:11], v[10:11], 0, v[2:3]
	v_lshl_add_u64 v[12:13], v[12:13], 4, s[2:3]
	v_lshl_add_u64 v[10:11], v[10:11], 4, s[2:3]
	global_load_dword v14, v[12:13], off sc1
	global_load_dword v15, v[10:11], off sc1
	global_load_dword v16, v[12:13], off offset:4 sc1
	global_load_dword v17, v[10:11], off offset:4 sc1
	global_load_dword v18, v[12:13], off offset:8 sc1
	global_load_dword v19, v[10:11], off offset:8 sc1
	s_nop 0
	global_load_dword v12, v[12:13], off offset:12 sc1
	s_nop 0
	global_load_dword v10, v[10:11], off offset:12 sc1
	v_cndmask_b32_e32 v11, v190, v191, vcc
	v_lshlrev_b32_e32 v11, 2, v11
	s_waitcnt vmcnt(5)
	v_add_f32_e32 v13, v14, v16
	s_waitcnt vmcnt(4)
	v_add_f32_e32 v14, v15, v17
	s_waitcnt vmcnt(1)
	v_add_f32_e32 v12, v18, v12
	s_waitcnt vmcnt(0)
	v_add_f32_e32 v10, v19, v10
	v_add_f32_e32 v12, v13, v12
	v_add_f32_e32 v10, v14, v10
	v_add_f32_e32 v10, v12, v10
	ds_bpermute_b32 v11, v11, v10
	s_and_saveexec_b64 s[12:13], s[6:7]
	s_cbranch_execz .LBB0_858
	s_waitcnt lgkmcnt(0)
	v_add_f32_e32 v10, v10, v11
	v_fmamk_f32 v10, v10, 0x3a800000, v188
	v_mul_f32_e32 v11, 0x4b800000, v10
	v_cmp_gt_f32_e32 vcc, s90, v10
	s_nop 1
	v_cndmask_b32_e32 v10, v10, v11, vcc
	v_rsq_f32_e32 v10, v10
	s_nop 0
	v_mul_f32_e32 v11, 0x45800000, v10
	v_cndmask_b32_e32 v10, v10, v11, vcc
	v_lshl_add_u32 v11, s15, 10, v9
	ds_write_b32 v11, v10
	s_branch .LBB0_858
